# baseline (speedup 1.0000x reference)
; __device__ __forceinline__ unsigned cvt_pk_bf16(float lo, float hi) { return __builtin_bit_cast(unsigned, __builtin_amdgcn_cvt_pkrtz(lo, hi)); }
; __device__ __forceinline__ void phase_ssm2(int wid_s, unsigned char* shm, const float* US, const float* SSA, const float* SSB, const float* FIN, const float* c_re, const float* c_im, const float* dvec, bf16_t* YG) {
;     ...
;         SsmProj P; ssm_proj_load(P, SSB, g, fr, fq);
;         bf16x8 cf[4];
; #pragma unroll
;         for (int ks = 0; ks < 4; ++ks) { const size_t o = ((size_t)g * 16 + fr) * 64 + 16 * ks + 4 * fq; const f32x4 cr = *(const f32x4*)(c_re + o), ci = *(const f32x4*)(c_im + o);
;             const u32x4 w = {cvt_pk_bf16(cr[0], -ci[0]), cvt_pk_bf16(cr[1], -ci[1]), cvt_pk_bf16(cr[2], -ci[2]), cvt_pk_bf16(cr[3], -ci[3])}; cf[ks] = __builtin_bit_cast(bf16x8, w); }
;         const f32x4 A = *(const f32x4*)(SSA + ((size_t)g * 64 + lane) * 4);
;         float sr = 0.f, si = 0.f;
;         for (int c0 = 0; c0 < ch; c0 += 8) {
;             f32x2 f[8];
; #pragma unroll
;             for (int j = 0; j < 8; ++j) { const int c = (c0 + j < NCH) ? c0 + j : NCH - 1; f[j] = *(const f32x2*)(FIN + ((size_t)((b * 32 + g) * NCH + c) * 64 + lane) * 2); }
; #pragma unroll
;             for (int j = 0; j < 8; ++j) if (c0 + j < ch) { const float nr = A[2] * sr - A[3] * si + f[j].x, ni = A[2] * si + A[3] * sr + f[j].y; sr = nr; si = ni; }
;         }
;         const f32x4 dv = *(const f32x4*)(dvec + g * 16 + 4 * fq);
;         u32x4 uw = ssm_u_load(US, (size_t)b * SEQ + ch * LCH, g, fr, fq);
.LBB0_492:
	s_or_b64 exec, exec, s[20:21]
	v_lshlrev_b32_e32 v0, 6, v3
	v_mov_b32_e32 v1, v2
	v_lshl_add_u64 v[0:1], v[86:87], 0, v[0:1]
	global_load_dwordx4 v[72:75], v[0:1], off
	s_ashr_i32 s19, s18, 31
	v_lshlrev_b32_e32 v0, 6, v77
	v_lshlrev_b32_e32 v104, 5, v3
	s_lshl_b64 s[6:7], s[18:19], 11
	v_ashrrev_i32_e32 v1, 31, v0
	v_lshl_add_u64 v[102:103], s[6:7], 0, v[0:1]
	v_mov_b32_e32 v126, 0
	v_mov_b32_e32 v127, 0
	v_mov_b32_e32 v128, 0
	v_mov_b32_e32 v129, 0
	s_and_saveexec_b64 s[6:7], s[4:5]
	s_cbranch_execz .Lp2_uw
	v_or_b32_e32 v0, v102, v80
	v_mov_b32_e32 v1, v103
	v_lshlrev_b64 v[0:1], 10, v[0:1]
	v_lshl_add_u64 v[0:1], s[16:17], 0, v[0:1]
	v_mov_b32_e32 v105, v2
	v_lshl_add_u64 v[0:1], v[0:1], 0, v[104:105]
	v_mov_b32_e32 v97, v2
	v_lshl_add_u64 v[0:1], v[0:1], 0, v[96:97]
	global_load_dwordx4 v[126:129], v[0:1], off
.Lp2_uw:
	s_or_b64 exec, exec, s[6:7]
	s_waitcnt vmcnt(0) lgkmcnt(0)
	v_mov_b32_e32 v3, v2
	v_mov_b32_e32 v76, v126
	v_mov_b32_e32 v77, v127
	v_mov_b32_e32 v78, v128
	v_mov_b32_e32 v79, v129
.LBB0_494:
	v_mov_b32_e32 v105, v2
	v_cvt_pkrtz_f16_f32 v56, v56, -v68
	v_cvt_pkrtz_f16_f32 v57, v57, -v69
	v_cvt_pkrtz_f16_f32 v58, v58, -v70
	v_cvt_pkrtz_f16_f32 v59, v59, -v71
	v_cvt_pkrtz_f16_f32 v52, v52, -v60
	v_cvt_pkrtz_f16_f32 v53, v53, -v61
	v_cvt_pkrtz_f16_f32 v54, v54, -v62
	v_cvt_pkrtz_f16_f32 v55, v55, -v63
	v_cvt_pkrtz_f16_f32 v44, v44, -v64
	v_cvt_pkrtz_f16_f32 v45, v45, -v65
	v_cvt_pkrtz_f16_f32 v46, v46, -v66
	v_cvt_pkrtz_f16_f32 v47, v47, -v67
	v_cvt_pkrtz_f16_f32 v38, v40, -v48
	v_cvt_pkrtz_f16_f32 v39, v41, -v49
	v_cvt_pkrtz_f16_f32 v40, v42, -v50
	v_cvt_pkrtz_f16_f32 v41, v43, -v51
	v_lshl_add_u64 v[0:1], v[88:89], 0, v[104:105]
	v_lshl_add_u64 v[42:43], v[90:91], 0, v[104:105]
	v_lshl_add_u64 v[60:61], v[92:93], 0, v[104:105]
	s_mov_b32 s18, 0
	s_waitcnt vmcnt(0)
	s_and_saveexec_b64 s[6:7], s[4:5]
	v_cvt_pkrtz_f16_f32 v8, v130, v131
	v_cvt_pkrtz_f16_f32 v9, v132, v133
	v_cvt_pkrtz_f16_f32 v10, v134, v135
	v_cvt_pkrtz_f16_f32 v11, v136, v137
	v_cvt_pkrtz_f16_f32 v12, v138, v139
	v_cvt_pkrtz_f16_f32 v13, v140, v141
	v_cvt_pkrtz_f16_f32 v14, v142, v143
	v_cvt_pkrtz_f16_f32 v15, v144, v145
	v_cvt_pkrtz_f16_f32 v4, v146, v147
	v_cvt_pkrtz_f16_f32 v5, v148, v149
	v_cvt_pkrtz_f16_f32 v6, v150, v151
	v_cvt_pkrtz_f16_f32 v7, v152, v153
	v_cvt_pkrtz_f16_f32 v16, v154, v155
	v_cvt_pkrtz_f16_f32 v17, v156, v157
	v_cvt_pkrtz_f16_f32 v18, v158, v159
	v_cvt_pkrtz_f16_f32 v19, v160, v161
	v_cvt_pkrtz_f16_f32 v24, v162, v163
	v_cvt_pkrtz_f16_f32 v25, v164, v165
	v_cvt_pkrtz_f16_f32 v26, v166, v167
	v_cvt_pkrtz_f16_f32 v27, v168, v169
	v_cvt_pkrtz_f16_f32 v28, v170, v171
	v_cvt_pkrtz_f16_f32 v29, v172, v173
	v_cvt_pkrtz_f16_f32 v30, v174, v175
	v_cvt_pkrtz_f16_f32 v31, v176, v177
	v_cvt_pkrtz_f16_f32 v20, v178, v179
	v_cvt_pkrtz_f16_f32 v21, v180, v181
	v_cvt_pkrtz_f16_f32 v22, v182, v183
	v_cvt_pkrtz_f16_f32 v23, v184, v185
	v_cvt_pkrtz_f16_f32 v32, v186, v187
	v_cvt_pkrtz_f16_f32 v33, v188, v189
	v_cvt_pkrtz_f16_f32 v34, v190, v191
	v_cvt_pkrtz_f16_f32 v35, v192, v193
	s_or_b64 exec, exec, s[6:7]
